# baseline (speedup 1.0000x reference)
.LBB0_217:
	s_setprio 3
	s_and_b32 s100, s0, 7
	s_lshl_b32 s100, s100, 6
	s_bfe_u32 s101, s0, 0x60003
	s_or_b32 s100, s100, s101
	s_and_b32 s101, s0, 0xfffffe00
	s_or_b32 s100, s100, s101
	s_cmpk_eq_u32 s66, 0x200
	s_cselect_b32 s100, s100, s0
	s_ashr_i32 s2, s100, 31
	s_lshr_b32 s2, s2, 29
	s_add_i32 s2, s100, s2
	s_ashr_i32 s6, s2, 3
	s_lshl_b32 s2, s6, 7
	s_lshl_b32 s7, s100, 7
	s_lshl_b32 s6, s6, 10
	v_add_u32_e32 v2, s2, v112
	s_sub_i32 s26, s7, s6
	v_ashrrev_i32_e32 v3, 31, v2
	v_lshlrev_b64 v[2:3], 11, v[2:3]
	v_add_u32_e32 v6, s26, v112
	v_lshl_add_u64 v[4:5], v[98:99], 0, v[2:3]
	v_ashrrev_i32_e32 v7, 31, v6
	v_lshlrev_b64 v[6:7], 11, v[6:7]
	v_add_co_u32_e32 v8, vcc, s31, v4
	v_lshl_add_u64 v[6:7], v[100:101], 0, v[6:7]
	s_nop 0
	v_addc_co_u32_e32 v9, vcc, 0, v5, vcc
	v_add_co_u32_e32 v10, vcc, s31, v6
	global_load_dwordx4 v[66:69], v[4:5], off
	global_load_dwordx4 v[70:73], v[6:7], off
	v_addc_co_u32_e32 v11, vcc, 0, v7, vcc
	global_load_dwordx4 v[74:77], v[8:9], off
	global_load_dwordx4 v[78:81], v[10:11], off
	v_add_co_u32_e32 v8, vcc, s33, v4
	s_waitcnt vmcnt(4)
	v_mov_b32_e32 v34, 0
	v_addc_co_u32_e32 v9, vcc, 0, v5, vcc
	v_add_co_u32_e32 v10, vcc, s33, v6
	v_lshl_add_u64 v[110:111], v[106:107], 0, v[2:3]
	s_nop 0
	v_addc_co_u32_e32 v11, vcc, 0, v7, vcc
	v_add_co_u32_e32 v4, vcc, s34, v4
	global_load_dwordx4 v[82:85], v[8:9], off
	global_load_dwordx4 v[86:89], v[10:11], off
	v_addc_co_u32_e32 v5, vcc, 0, v5, vcc
	v_add_co_u32_e32 v6, vcc, 0x30000, v6
	v_mov_b32_e32 v35, v34
	s_nop 0
	v_addc_co_u32_e32 v7, vcc, 0, v7, vcc
	global_load_dwordx4 v[90:93], v[4:5], off
	global_load_dwordx4 v[94:97], v[6:7], off
	v_add_u32_e32 v4, s26, v112
	v_ashrrev_i32_e32 v5, 31, v4
	v_lshlrev_b64 v[4:5], 11, v[4:5]
	v_lshl_add_u64 v[108:109], v[104:105], 0, v[4:5]
	s_mov_b64 s[6:7], 0
	s_waitcnt lgkmcnt(0)
	v_mov_b32_e32 v36, v34
	v_mov_b32_e32 v37, v34
	v_mov_b32_e32 v38, v34
	v_mov_b32_e32 v39, v34
	v_mov_b32_e32 v40, v34
	v_mov_b32_e32 v41, v34
	v_mov_b32_e32 v42, v34
	v_mov_b32_e32 v43, v34
	v_mov_b32_e32 v44, v34
	v_mov_b32_e32 v45, v34
	v_mov_b32_e32 v50, v34
	v_mov_b32_e32 v51, v34
	v_mov_b32_e32 v52, v34
	v_mov_b32_e32 v53, v34
	v_mov_b32_e32 v62, v34
	v_mov_b32_e32 v63, v34
	v_mov_b32_e32 v64, v34
	v_mov_b32_e32 v65, v34
	v_mov_b32_e32 v58, v34
	v_mov_b32_e32 v59, v34
	v_mov_b32_e32 v60, v34
	v_mov_b32_e32 v61, v34
	v_mov_b32_e32 v54, v34
	v_mov_b32_e32 v55, v34
	v_mov_b32_e32 v56, v34
	v_mov_b32_e32 v57, v34
	v_mov_b32_e32 v46, v34
	v_mov_b32_e32 v47, v34
	v_mov_b32_e32 v48, v34
	v_mov_b32_e32 v49, v34
	v_mov_b32_e32 v30, v34
	v_mov_b32_e32 v31, v34
	v_mov_b32_e32 v32, v34
	v_mov_b32_e32 v33, v34
	v_mov_b32_e32 v26, v34
	v_mov_b32_e32 v27, v34
	v_mov_b32_e32 v28, v34
	v_mov_b32_e32 v29, v34
	v_mov_b32_e32 v18, v34
	v_mov_b32_e32 v19, v34
	v_mov_b32_e32 v20, v34
	v_mov_b32_e32 v21, v34
	v_mov_b32_e32 v14, v34
	v_mov_b32_e32 v15, v34
	v_mov_b32_e32 v16, v34
	v_mov_b32_e32 v17, v34
	v_mov_b32_e32 v22, v34
	v_mov_b32_e32 v23, v34
	v_mov_b32_e32 v24, v34
	v_mov_b32_e32 v25, v34
	v_mov_b32_e32 v6, v34
	v_mov_b32_e32 v7, v34
	v_mov_b32_e32 v8, v34
	v_mov_b32_e32 v9, v34
	v_mov_b32_e32 v2, v34
	v_mov_b32_e32 v3, v34
	v_mov_b32_e32 v4, v34
	v_mov_b32_e32 v5, v34
	v_mov_b32_e32 v10, v34
	v_mov_b32_e32 v11, v34
	v_mov_b32_e32 v12, v34
	v_mov_b32_e32 v13, v34
	s_mov_b32 s38, 0x27d0000

.LBB0_241:
	s_setprio 3
	s_and_b32 s100, s2, 7
	s_lshl_b32 s100, s100, 6
	s_bfe_u32 s101, s2, 0x60003
	s_or_b32 s100, s100, s101
	s_and_b32 s101, s2, 0xfffffe00
	s_or_b32 s100, s100, s101
	s_cmpk_eq_u32 s66, 0x200
	s_cselect_b32 s100, s100, s2
	s_ashr_i32 s0, s100, 31
	s_lshr_b32 s0, s0, 29
	s_add_i32 s0, s100, s0
	s_ashr_i32 s6, s0, 3
	s_lshl_b32 s0, s6, 7
	s_lshl_b32 s7, s100, 7
	s_lshl_b32 s6, s6, 10
	v_add_u32_e32 v2, s0, v112
	s_sub_i32 s26, s7, s6
	v_ashrrev_i32_e32 v3, 31, v2
	v_lshlrev_b64 v[2:3], 11, v[2:3]
	v_add_u32_e32 v6, s26, v112
	v_lshl_add_u64 v[4:5], v[98:99], 0, v[2:3]
	v_ashrrev_i32_e32 v7, 31, v6
	v_lshlrev_b64 v[6:7], 11, v[6:7]
	v_add_co_u32_e32 v8, vcc, s31, v4
	v_lshl_add_u64 v[6:7], v[100:101], 0, v[6:7]
	s_nop 0
	v_addc_co_u32_e32 v9, vcc, 0, v5, vcc
	v_add_co_u32_e32 v10, vcc, s31, v6
	global_load_dwordx4 v[70:73], v[4:5], off
	global_load_dwordx4 v[66:69], v[6:7], off
	v_addc_co_u32_e32 v11, vcc, 0, v7, vcc
	global_load_dwordx4 v[74:77], v[8:9], off
	global_load_dwordx4 v[78:81], v[10:11], off
	v_add_co_u32_e32 v8, vcc, s33, v4
	v_mov_b32_e32 v38, 0
	s_nop 0
	v_addc_co_u32_e32 v9, vcc, 0, v5, vcc
	v_add_co_u32_e32 v10, vcc, s33, v6
	v_lshl_add_u64 v[110:111], v[106:107], 0, v[2:3]
	s_nop 0
	v_addc_co_u32_e32 v11, vcc, 0, v7, vcc
	v_add_co_u32_e32 v4, vcc, s34, v4
	global_load_dwordx4 v[82:85], v[8:9], off
	global_load_dwordx4 v[86:89], v[10:11], off
	v_addc_co_u32_e32 v5, vcc, 0, v5, vcc
	v_add_co_u32_e32 v6, vcc, 0x30000, v6
	v_mov_b32_e32 v39, v38
	s_nop 0
	v_addc_co_u32_e32 v7, vcc, 0, v7, vcc
	global_load_dwordx4 v[90:93], v[4:5], off
	global_load_dwordx4 v[94:97], v[6:7], off
	v_add_u32_e32 v4, s26, v112
	v_ashrrev_i32_e32 v5, 31, v4
	v_lshlrev_b64 v[4:5], 11, v[4:5]
	v_lshl_add_u64 v[108:109], v[104:105], 0, v[4:5]
	s_mov_b64 s[6:7], 0
	v_mov_b32_e32 v40, v38
	v_mov_b32_e32 v41, v38
	v_mov_b32_e32 v46, v38
	v_mov_b32_e32 v47, v38
	v_mov_b32_e32 v48, v38
	v_mov_b32_e32 v49, v38
	v_mov_b32_e32 v54, v38
	v_mov_b32_e32 v55, v38
	v_mov_b32_e32 v56, v38
	v_mov_b32_e32 v57, v38
	v_mov_b32_e32 v62, v38
	v_mov_b32_e32 v63, v38
	v_mov_b32_e32 v64, v38
	v_mov_b32_e32 v65, v38
	v_mov_b32_e32 v58, v38
	v_mov_b32_e32 v59, v38
	v_mov_b32_e32 v60, v38
	v_mov_b32_e32 v61, v38
	v_mov_b32_e32 v50, v38
	v_mov_b32_e32 v51, v38
	v_mov_b32_e32 v52, v38
	v_mov_b32_e32 v53, v38
	v_mov_b32_e32 v42, v38
	v_mov_b32_e32 v43, v38
	v_mov_b32_e32 v44, v38
	v_mov_b32_e32 v45, v38
	s_waitcnt vmcnt(8)
	v_mov_b32_e32 v34, v38
	v_mov_b32_e32 v35, v38
	v_mov_b32_e32 v36, v38
	v_mov_b32_e32 v37, v38
	v_mov_b32_e32 v30, v38
	v_mov_b32_e32 v31, v38
	v_mov_b32_e32 v32, v38
	v_mov_b32_e32 v33, v38
	v_mov_b32_e32 v18, v38
	v_mov_b32_e32 v19, v38
	v_mov_b32_e32 v20, v38
	v_mov_b32_e32 v21, v38
	v_mov_b32_e32 v22, v38
	v_mov_b32_e32 v23, v38
	v_mov_b32_e32 v24, v38
	v_mov_b32_e32 v25, v38
	v_mov_b32_e32 v26, v38
	v_mov_b32_e32 v27, v38
	v_mov_b32_e32 v28, v38
	v_mov_b32_e32 v29, v38
	v_mov_b32_e32 v6, v38
	v_mov_b32_e32 v7, v38
	v_mov_b32_e32 v8, v38
	v_mov_b32_e32 v9, v38
	v_mov_b32_e32 v2, v38
	v_mov_b32_e32 v3, v38
	v_mov_b32_e32 v4, v38
	v_mov_b32_e32 v5, v38
	v_mov_b32_e32 v10, v38
	v_mov_b32_e32 v11, v38
	v_mov_b32_e32 v12, v38
	v_mov_b32_e32 v13, v38
	v_mov_b32_e32 v14, v38
	v_mov_b32_e32 v15, v38
	v_mov_b32_e32 v16, v38
	v_mov_b32_e32 v17, v38

.LBB0_253:
	s_setprio 3
	s_lshr_b32 s2, s84, 3
	s_cmpk_gt_u32 s84, 0x1ff
	s_mov_b64 s[6:7], -1
	s_cbranch_scc0 .LBB0_259
	s_and_b32 s8, s2, 63
	s_ashr_i32 s9, s84, 9
	s_cmp_lg_u32 s9, 1
	s_cbranch_scc0 .LBB0_256
	s_or_b32 s0, s8, 64
	s_cmp_eq_u32 s9, 2
	s_cselect_b32 s0, s8, s0
	s_mov_b64 s[6:7], 0

.LBB0_267:
	s_setprio 3
	s_cmp_gt_u32 s2, 1
	s_cselect_b64 s[12:13], -1, 0
	s_cmp_eq_u32 s2, 2
	s_cselect_b64 s[14:15], -1, 0
	s_cmp_lt_u32 s2, 2
	s_cselect_b64 s[18:19], -1, 0
	s_and_b64 s[6:7], s[18:19], exec
	s_cselect_b32 s74, 0, s91
	s_cmp_lg_u32 s2, 2
	s_mov_b32 s0, s93
	s_cbranch_scc1 .LBB0_274
	ds_read_b32 v0, v1 offset:54272
	s_waitcnt lgkmcnt(0)
	v_cmp_ne_u32_e32 vcc, 0, v0
	v_readfirstlane_b32 s0, v0
	s_cbranch_vccz .LBB0_270
	s_ff1_i32_b32 s74, s0
	s_branch .LBB0_273

.LBB0_768:
	s_setprio 3
	s_lshl_b32 s0, s8, 9
	s_ashr_i32 s13, s8, 5
	s_and_b32 s0, s0, 0x2000
	s_lshl_b32 s9, s13, 7
	s_lshl_b32 s12, s13, 1
	s_mul_i32 s2, s0, 0x1800
	v_readlane_b32 s6, v255, 19
	v_readlane_b32 s7, v255, 20
	s_add_u32 s10, s6, s2
	s_addc_u32 s11, s7, 0
	s_lshl_b32 s2, s8, 6
	s_and_b32 s2, s2, 0x3c0
	s_lshl_b32 s2, s2, 1
	s_add_u32 s6, s10, s2
	s_addc_u32 s7, s11, 0
	s_or_b32 s35, s12, 1
	s_lshl_b32 s16, s35, 6
	v_add_u32_e32 v4, s16, v156
	v_mov_b64_e32 v[2:3], s[10:11]
	s_movk_i32 s17, 0x1800
	v_mad_i64_i32 v[4:5], s[14:15], v4, s17, v[2:3]
	v_lshl_add_u64 v[4:5], v[4:5], 0, s[2:3]
	v_mov_b32_e32 v103, v1
	v_lshl_add_u64 v[4:5], v[4:5], 0, v[102:103]
	s_mov_b64 s[18:19], 0x800
	v_lshl_add_u64 v[6:7], v[4:5], 0, s[18:19]
	global_load_dwordx4 v[10:13], v[4:5], off offset:2048
	global_load_dwordx4 v[22:25], v[6:7], off offset:2048
	v_add_u32_e32 v4, s16, v157
	v_mov_b32_e32 v101, v1
	v_mad_i64_i32 v[2:3], s[14:15], v4, s17, v[2:3]
	v_add_u32_e32 v0, s9, v94
	s_waitcnt vmcnt(11)
	v_lshl_add_u64 v[14:15], s[6:7], 0, v[100:101]
	v_lshl_add_u64 v[2:3], v[2:3], 0, s[2:3]
	v_lshl_add_u64 v[2:3], v[2:3], 0, v[102:103]
	v_mad_i64_i32 v[6:7], s[14:15], v0, s17, v[14:15]
	v_or_b32_e32 v0, 16, v0
	v_lshl_add_u64 v[4:5], v[2:3], 0, s[18:19]
	s_waitcnt vmcnt(10)
	v_mad_i64_i32 v[18:19], s[14:15], v0, s17, v[14:15]
	global_load_dwordx4 v[26:29], v[2:3], off offset:2048
	global_load_dwordx4 v[30:33], v[4:5], off offset:2048
	s_nop 0
	global_load_dwordx4 v[2:5], v[6:7], off
	s_nop 0
	global_load_dwordx4 v[6:9], v[6:7], off offset:64
	s_nop 0
	global_load_dwordx4 v[14:17], v[18:19], off
	s_nop 0
	global_load_dwordx4 v[18:21], v[18:19], off offset:64
	v_add_u32_e32 v0, v125, v158
	s_cmp_lt_i32 s13, 0
	v_add_u32_e32 v34, v125, v161
	s_waitcnt vmcnt(7)
	ds_write_b128 v0, v[10:13]
	s_waitcnt vmcnt(6)
	ds_write_b16 v160, v22 offset:9216
	ds_write_b16_d16_hi v160, v22 offset:9360
	ds_write_b16 v160, v23 offset:9504
	ds_write_b16_d16_hi v160, v23 offset:9648
	ds_write_b16 v160, v24 offset:9792
	ds_write_b16_d16_hi v160, v24 offset:9936
	ds_write_b16 v160, v25 offset:10080
	ds_write_b16_d16_hi v160, v25 offset:10224
	s_waitcnt vmcnt(5)
	ds_write_b128 v34, v[26:29]
	s_waitcnt vmcnt(4)
	ds_write_b16 v163, v30 offset:9216
	ds_write_b16_d16_hi v163, v30 offset:9360
	ds_write_b16 v163, v31 offset:9504
	ds_write_b16_d16_hi v163, v31 offset:9648
	ds_write_b16 v163, v32 offset:9792
	ds_write_b16_d16_hi v163, v32 offset:9936
	ds_write_b16 v163, v33 offset:10080
	ds_write_b16_d16_hi v163, v33 offset:10224
	s_cbranch_scc1 .LBB0_770
	v_add_u32_e32 v0, s9, v156
	v_mov_b64_e32 v[26:27], s[10:11]
	v_mad_i64_i32 v[10:11], s[10:11], v0, s17, v[26:27]
	v_add_u32_e32 v0, s9, v157
	v_mad_i64_i32 v[26:27], s[10:11], v0, s17, v[26:27]
	v_lshl_add_u64 v[10:11], v[10:11], 0, s[2:3]
	v_lshl_add_u64 v[26:27], v[26:27], 0, s[2:3]
	v_lshl_add_u64 v[10:11], v[10:11], 0, v[102:103]
	v_lshl_add_u64 v[26:27], v[26:27], 0, v[102:103]
	v_lshl_add_u64 v[22:23], v[10:11], 0, s[18:19]
	v_lshl_add_u64 v[30:31], v[26:27], 0, s[18:19]
	global_load_dwordx4 v[10:13], v[10:11], off offset:2048
	s_nop 0
	global_load_dwordx4 v[22:25], v[22:23], off offset:2048
	s_nop 0
	global_load_dwordx4 v[26:29], v[26:27], off offset:2048
	s_nop 0
	global_load_dwordx4 v[30:33], v[30:31], off offset:2048

.LBB0_791:
	s_setprio 3
	s_cmpk_lg_u32 s66, 0x200
	s_cbranch_scc1 .Lip_noremap
	s_and_b32 s0, s14, 7
	s_bfe_u32 s6, s14, 0x60003
	s_lshr_b32 s7, s14, 9
	s_lshl_b32 s7, s7, 6
	s_add_i32 s6, s6, s7
	s_mul_i32 s7, s2, 0x5556
	s_lshr_b32 s7, s7, 16
	s_lshl_b32 s8, s7, 3
	s_cmp_eq_u32 s8, 64
	s_movk_i32 s9, 0x493
	s_cselect_b32 s9, 0x400, s9
	s_mul_i32 s9, s6, s9
	s_lshr_b32 s9, s9, 16
	s_mul_i32 s101, s9, s8
	s_sub_i32 s6, s6, s101
	s_cmp_eq_u32 s7, 8
	s_movk_i32 s101, 0x2493
	s_cselect_b32 s101, 0x2000, s101
	s_mul_i32 s101, s6, s101
	s_lshr_b32 s101, s101, 16
	s_mul_i32 s8, s101, s7
	s_sub_i32 s6, s6, s8
	s_cmp_ge_u32 s9, 3
	s_cselect_b32 s8, 1, 0
	s_mul_i32 s100, s8, 3
	s_sub_i32 s9, s9, s100
	s_sub_i32 s100, 2, s9
	s_cmp_eq_u32 s8, 1
	s_cselect_b32 s9, s100, s9
	s_lshl_b32 s0, s0, 4
	s_lshl_b32 s8, s8, 3
	s_add_i32 s0, s0, s8
	s_add_i32 s0, s0, s101
	s_mul_i32 s9, s9, s7
	s_add_i32 s9, s9, s6
	s_mul_i32 s100, s0, s2
	s_add_i32 s100, s100, s9
	s_branch .Lip_go
